# dn_prep: EK table (expf(g63-Gs[t]) computed once by wave 0, tile writers load it instead of 8 expf per fragment) plus s_setprio 3 for the five forward-substitution waves during step 4
# speedup vs baseline: 1.0022x; 1.0022x over previous
; DI void dn_prep_item(const Params& p, int l, int item, int next_item, u32x4 (&pre)[12], unsigned char* lds, int tid) {
;     ...
;     if (tid < 64) {
;         const float a = da_raw + dtb, bb = db_raw;
;         const float sp = (a > 20.f) ? a : ((a < -15.f) ? expf(a) : logf(1.f + expf(a)));
;         float x = -expf(alog) * sp;
; #pragma unroll
;         for (int o = 1; o < 64; o <<= 1) { const float v = __shfl_up(x, o); if (lane >= o) x += v; }
;         Gs[tid] = x; BETAs[tid] = 1.f / (1.f + expf(-bb)); EGs[tid] = expf(x);
;     }
.LBB0_314:
	s_or_b64 exec, exec, s[10:11]
	v_add_u32_e32 v6, -1, v206
	v_cmp_lt_i32_e32 vcc, v6, v35
	v_mul_f32_e64 v5, v4, -v80
	v_add_u32_e32 v7, -2, v206
	v_cndmask_b32_e32 v6, v6, v206, vcc
	v_lshlrev_b32_e32 v6, 2, v6
	ds_bpermute_b32 v6, v6, v5
	v_cmp_eq_u32_e32 vcc, 0, v30
	s_waitcnt lgkmcnt(0)
	v_fma_f32 v4, v4, -v80, v6
	v_cndmask_b32_e32 v4, v4, v5, vcc
	v_cmp_lt_i32_e32 vcc, v7, v35
	v_mul_f32_e32 v6, 0xbfb8aa3b, v78
	s_nop 0
	v_cndmask_b32_e32 v5, v7, v206, vcc
	v_lshlrev_b32_e32 v5, 2, v5
	ds_bpermute_b32 v5, v5, v4
	v_cmp_gt_u32_e32 vcc, 2, v30
	v_rndne_f32_e32 v7, v6
	v_sub_f32_e32 v8, v6, v7
	v_fma_f32 v6, v78, s58, -v6
	s_waitcnt lgkmcnt(0)
	v_add_f32_e32 v5, v4, v5
	v_cndmask_b32_e32 v4, v5, v4, vcc
	v_add_u32_e32 v5, -4, v206
	v_cmp_lt_i32_e32 vcc, v5, v35
	v_fmac_f32_e32 v6, 0xb2a5705f, v78
	v_add_f32_e32 v6, v8, v6
	v_cndmask_b32_e32 v5, v5, v206, vcc
	v_lshlrev_b32_e32 v5, 2, v5
	ds_bpermute_b32 v5, v5, v4
	v_cmp_gt_u32_e32 vcc, 4, v30
	v_exp_f32_e32 v6, v6
	v_cvt_i32_f32_e32 v7, v7
	v_lshlrev_b32_e32 v8, 2, v54
	s_waitcnt lgkmcnt(0)
	v_add_f32_e32 v5, v4, v5
	v_cndmask_b32_e32 v4, v5, v4, vcc
	v_add_u32_e32 v5, -8, v206
	v_cmp_lt_i32_e32 vcc, v5, v35
	v_add_u32_e32 v9, v68, v8
	s_nop 0
	v_cndmask_b32_e32 v5, v5, v206, vcc
	v_lshlrev_b32_e32 v5, 2, v5
	ds_bpermute_b32 v5, v5, v4
	v_cmp_gt_u32_e32 vcc, 8, v30
	s_waitcnt lgkmcnt(0)
	v_add_f32_e32 v5, v4, v5
	v_cndmask_b32_e32 v4, v5, v4, vcc
	v_add_u32_e32 v5, -16, v206
	v_cmp_lt_i32_e32 vcc, v5, v35
	s_nop 1
	v_cndmask_b32_e32 v5, v5, v206, vcc
	v_lshlrev_b32_e32 v5, 2, v5
	ds_bpermute_b32 v5, v5, v4
	v_cmp_gt_u32_e32 vcc, 16, v30
	s_waitcnt lgkmcnt(0)
	v_add_f32_e32 v5, v4, v5
	v_cndmask_b32_e32 v4, v5, v4, vcc
	v_subrev_u32_e32 v5, 32, v206
	v_cmp_lt_i32_e32 vcc, v5, v35
	s_nop 1
	v_cndmask_b32_e32 v5, v5, v206, vcc
	v_lshlrev_b32_e32 v5, 2, v5
	ds_bpermute_b32 v5, v5, v4
	v_cmp_gt_u32_e32 vcc, 32, v30
	s_waitcnt lgkmcnt(0)
	v_add_f32_e32 v5, v4, v5
	v_cndmask_b32_e32 v4, v5, v4, vcc
	v_ldexp_f32 v5, v6, v7
	v_cmp_nlt_f32_e32 vcc, s59, v78
	ds_write_b32 v9, v4
	v_mov_b32_e32 v212, v4
	s_nop 0
	v_cndmask_b32_e32 v5, 0, v5, vcc
	v_cmp_ngt_f32_e32 vcc, s55, v78
	s_nop 1
	v_cndmask_b32_e32 v5, v210, v5, vcc
	v_add_f32_e32 v5, 1.0, v5
	v_div_scale_f32 v6, s[6:7], v5, v5, 1.0
	v_rcp_f32_e32 v7, v6
	s_nop 0
	v_fma_f32 v9, -v6, v7, 1.0
	v_fmac_f32_e32 v7, v9, v7
	v_div_scale_f32 v9, vcc, 1.0, v5, 1.0
	v_mul_f32_e32 v10, v9, v7
	v_fma_f32 v11, -v6, v10, v9
	v_fmac_f32_e32 v10, v11, v7
	v_fma_f32 v6, -v6, v10, v9
	v_div_fmas_f32 v6, v6, v7, v10
	v_mul_f32_e32 v7, 0x3fb8aa3b, v4
	v_fma_f32 v9, v4, s88, -v7
	v_rndne_f32_e32 v10, v7
	v_fmac_f32_e32 v9, 0x32a5705f, v4
	v_sub_f32_e32 v7, v7, v10
	v_add_f32_e32 v7, v7, v9
	v_exp_f32_e32 v7, v7
	v_cvt_i32_f32_e32 v9, v10
	v_div_fixup_f32 v5, v6, v5, 1.0
	v_add_u32_e32 v6, v69, v8
	ds_write_b32 v6, v5
	v_ldexp_f32 v5, v7, v9
	v_cmp_ngt_f32_e32 vcc, s79, v4
	s_nop 1
	v_cndmask_b32_e32 v5, 0, v5, vcc
	v_cmp_nlt_f32_e32 vcc, s54, v4
	s_nop 1
	v_cndmask_b32_e32 v4, v210, v5, vcc
	v_add_u32_e32 v5, v70, v8
	ds_write_b32 v5, v4
	v_readlane_b32 s5, v212, 63
	s_nop 1
	v_sub_f32_e32 v213, s5, v212
	v_mul_f32_e32 v214, 0x3fb8aa3b, v213
	v_fma_f32 v215, v213, s88, -v214
	v_rndne_f32_e32 v212, v214
	v_fmac_f32_e32 v215, 0x32a5705f, v213
	v_sub_f32_e32 v214, v214, v212
	v_add_f32_e32 v214, v214, v215
	v_exp_f32_e32 v214, v214
	v_cvt_i32_f32_e32 v212, v212
	v_cmp_ngt_f32_e32 vcc, s79, v213
	v_ldexp_f32 v214, v214, v212
	v_add_u32_e32 v215, 0xa500, v8
	v_cndmask_b32_e32 v214, 0, v214, vcc
	v_cmp_nlt_f32_e32 vcc, s54, v213
	v_add_u32_e32 v215, v68, v215
	s_nop 0
	v_cndmask_b32_e32 v214, v210, v214, vcc
	ds_write_b32 v215, v214

; DI unsigned pk2(float lo, float hi) { f32x2_t v = {lo, hi}; bf16x2_t b = __builtin_convertvector(v, bf16x2_t); return __builtin_bit_cast(unsigned, b); }
; DI void dn_prep_item(const Params& p, int l, int item, int next_item, u32x4 (&pre)[12], unsigned char* lds, int tid) {
;     ...
;             for (int q = wv - 5; q < 24; q += 3) { const int mat = q >> 3, f = q & 7, m = f >> 1, s = f & 1, row = 16 * m + r, c0 = 32 * s + 4 * g, c1 = c0 + 16;
;                 float v[8];
;                 if (mat == 0) { const float eg = EGs[row]; const float* a = Qs + row * 65;
; #pragma unroll
;                     for (int e = 0; e < 4; ++e) { v[e] = a[c0 + e] * eg; v[4 + e] = a[c1 + e] * eg; } }
;                 else if (mat == 1) { const float* a = AIs + row * 64;
; #pragma unroll
;                     for (int e = 0; e < 4; ++e) { v[e] = a[c0 + e]; v[4 + e] = a[c1 + e]; } }
;                 else {
; #pragma unroll
;                     for (int e = 0; e < 4; ++e) { v[e] = Ks[(c0 + e) * 65 + row] * expf(g63 - Gs[c0 + e]); v[4 + e] = Ks[(c1 + e) * 65 + row] * expf(g63 - Gs[c1 + e]); } }
;                 u32x4 w; w.x = pk2(v[0], v[1]); w.y = pk2(v[2], v[3]); w.z = pk2(v[4], v[5]); w.w = pk2(v[6], v[7]);
;                 *(u32x4*)(base_ + 8192 * (mat + 1) + (size_t)(f * 64 + lane) * 16) = w; }
.LBB0_354:
	v_add_u32_e32 v11, 3, v11
	v_lshlrev_b32_e32 v0, 3, v11
	v_lshrrev_b32_e32 v13, 3, v11
	v_and_or_b32 v14, v0, 48, v61
	v_and_or_b32 v15, v12, 32, v8
	v_cmp_lt_u32_e32 vcc, 7, v11
	s_and_saveexec_b64 s[22:23], vcc
	s_xor_b64 s[34:35], exec, s[22:23]
	s_cbranch_execz .LBB0_360
	v_cmp_ne_u32_e32 vcc, 1, v13
	s_and_saveexec_b64 s[22:23], vcc
	s_xor_b64 s[36:37], exec, s[22:23]
	s_cbranch_execz .LBB0_357
	v_lshl_add_u32 v6, v15, 2, v68
	v_add_u32_e32 v6, 0xa500, v6
	v_mul_u32_u24_e32 v16, 0x104, v15
	v_lshlrev_b32_e32 v14, 2, v14
	v_add3_u32 v20, v168, v16, v14
	ds_read2_b32 v[0:1], v6 offset1:1
	ds_read2_b32 v[2:3], v6 offset0:16 offset1:17
	ds_read2_b32 v[4:5], v6 offset0:2 offset1:3
	ds_read2_b32 v[22:23], v6 offset0:18 offset1:19
	v_add_u32_e32 v14, 0x4000, v20
	v_add_u32_e32 v16, 0x5000, v20
	v_add_u32_e32 v18, 0x4200, v20
	v_add_u32_e32 v6, 0x5200, v20
	ds_read2_b32 v[14:15], v14 offset0:64 offset1:129
	ds_read2_b32 v[16:17], v16 offset0:80 offset1:145
	ds_read2_b32 v[18:19], v18 offset0:66 offset1:131
	ds_read2_b32 v[20:21], v6 offset0:82 offset1:147
	s_waitcnt lgkmcnt(0)
	v_pk_mul_f32 v[2:3], v[16:17], v[2:3]
	v_pk_mul_f32 v[4:5], v[18:19], v[4:5]
	v_pk_mul_f32 v[6:7], v[14:15], v[0:1]
	v_pk_mul_f32 v[0:1], v[20:21], v[22:23]

; DI void dn_prep_item(const Params& p, int l, int item, int next_item, u32x4 (&pre)[12], unsigned char* lds, int tid) {
;     ...
;         if (wv < 5) {
;             const int half = (wv >= 2) ? 1 : 0, c = (wv < 2) ? tid : ((wv < 4) ? tid - 128 : (lane & 31)), r0 = 32 * half;
;             const float* Lb = Ls + r0 * 64 + r0;
;             float x[32];
;             if (wv < 4) {
; #pragma unroll
;                 for (int i = 0; i < 32; ++i) x[i] = (c < 64) ? BETAs[r0 + i] * Vs[(r0 + i) * 65 + c] : BETAs[r0 + i] * Ks[(r0 + i) * 65 + c - 64] * EGs[r0 + i];
;             } else {
; #pragma unroll
;                 for (int i = 0; i < 32; ++i) x[i] = Ls[(32 + i) * 64 + c];
;             }
.LBB0_363:
	s_or_saveexec_b64 s[8:9], s[8:9]
	v_mov_b64_e32 v[0:1], s[10:11]
	v_mov_b64_e32 v[58:59], s[6:7]
	s_xor_b64 exec, exec, s[8:9]
	s_cbranch_execz .LBB0_503
	s_setprio 3
	v_add_u32_e32 v0, 0xffffff80, v54
	v_and_b32_e32 v31, 31, v54
	v_cmp_eq_u32_e64 s[6:7], 4, v60
	v_cmp_ne_u32_e32 vcc, 4, v60
	s_nop 0
	v_cndmask_b32_e64 v0, v0, v31, s[6:7]
	v_cmp_gt_i32_e64 s[6:7], 2, v60
	s_nop 1
	v_cndmask_b32_e64 v32, v0, v54, s[6:7]
	v_cmp_lt_i32_e64 s[6:7], 1, v60
	s_nop 1
	v_cndmask_b32_e64 v33, 0, 32, s[6:7]
	v_lshlrev_b32_e32 v0, 8, v33
	v_lshlrev_b32_e32 v1, 2, v33
	v_add3_u32 v35, v168, v0, v1
	s_and_saveexec_b64 s[6:7], vcc
	s_xor_b64 s[10:11], exec, s[6:7]
	s_cbranch_execz .LBB0_494
	s_movk_i32 s5, 0x41
	v_cmp_lt_i32_e64 s[12:13], 63, v32
	v_mad_u32_u24 v244, v33, s5, v32
	v_lshl_add_u32 v245, v33, 2, v69
	v_lshl_add_u32 v246, v33, 2, v70
	v_mov_b32_e32 v247, 0x8200
	v_mov_b32_e32 v248, 0x4000
	v_lshl_add_u32 v244, v244, 2, v168
	v_cndmask_b32_e64 v247, v247, v248, s[12:13]
	v_add_u32_e32 v244, v244, v247
	ds_read_b128 v[212:215], v245
	ds_read_b128 v[216:219], v245 offset:16
	ds_read_b128 v[220:223], v245 offset:32
	ds_read_b128 v[224:227], v245 offset:48
	ds_read_b128 v[228:231], v245 offset:64
	ds_read_b128 v[232:235], v245 offset:80
	ds_read_b128 v[236:239], v245 offset:96
	ds_read_b128 v[240:243], v245 offset:112
	ds_read_b32 v0, v244
	ds_read_b32 v1, v244 offset:260
	ds_read_b32 v2, v244 offset:520
	ds_read_b32 v3, v244 offset:780
	ds_read_b32 v4, v244 offset:1040
	ds_read_b32 v5, v244 offset:1300
	ds_read_b32 v6, v244 offset:1560
	ds_read_b32 v7, v244 offset:1820
	ds_read_b32 v8, v244 offset:2080
	ds_read_b32 v9, v244 offset:2340
	ds_read_b32 v10, v244 offset:2600
	ds_read_b32 v11, v244 offset:2860
	ds_read_b32 v12, v244 offset:3120
	ds_read_b32 v13, v244 offset:3380
	ds_read_b32 v14, v244 offset:3640
	ds_read_b32 v15, v244 offset:3900
	ds_read_b32 v16, v244 offset:4160
	ds_read_b32 v17, v244 offset:4420
	ds_read_b32 v18, v244 offset:4680
	ds_read_b32 v19, v244 offset:4940
	ds_read_b32 v20, v244 offset:5200
	ds_read_b32 v21, v244 offset:5460
	ds_read_b32 v22, v244 offset:5720
	ds_read_b32 v23, v244 offset:5980
	ds_read_b32 v24, v244 offset:6240
	ds_read_b32 v25, v244 offset:6500
	ds_read_b32 v26, v244 offset:6760
	ds_read_b32 v27, v244 offset:7020
	ds_read_b32 v36, v244 offset:7280
	ds_read_b32 v28, v244 offset:7540
	ds_read_b32 v29, v244 offset:7800
	ds_read_b32 v37, v244 offset:8060
	s_waitcnt lgkmcnt(0)
	v_mul_f32_e32 v0, v212, v0
	v_mul_f32_e32 v1, v213, v1
	v_mul_f32_e32 v2, v214, v2
	v_mul_f32_e32 v3, v215, v3
	v_mul_f32_e32 v4, v216, v4
	v_mul_f32_e32 v5, v217, v5
	v_mul_f32_e32 v6, v218, v6
	v_mul_f32_e32 v7, v219, v7
	v_mul_f32_e32 v8, v220, v8
	v_mul_f32_e32 v9, v221, v9
	v_mul_f32_e32 v10, v222, v10
	v_mul_f32_e32 v11, v223, v11
	v_mul_f32_e32 v12, v224, v12
	v_mul_f32_e32 v13, v225, v13
	v_mul_f32_e32 v14, v226, v14
	v_mul_f32_e32 v15, v227, v15
	v_mul_f32_e32 v16, v228, v16
	v_mul_f32_e32 v17, v229, v17
	v_mul_f32_e32 v18, v230, v18
	v_mul_f32_e32 v19, v231, v19
	v_mul_f32_e32 v20, v232, v20
	v_mul_f32_e32 v21, v233, v21
	v_mul_f32_e32 v22, v234, v22
	v_mul_f32_e32 v23, v235, v23
	v_mul_f32_e32 v24, v236, v24
	v_mul_f32_e32 v25, v237, v25
	v_mul_f32_e32 v26, v238, v26
	v_mul_f32_e32 v27, v239, v27
	v_mul_f32_e32 v36, v240, v36
	v_mul_f32_e32 v28, v241, v28
	v_mul_f32_e32 v29, v242, v29
	v_mul_f32_e32 v37, v243, v37
	s_cmp_eq_u64 s[12:13], 0
	s_cbranch_scc1 .Lxinit_done
	ds_read_b128 v[212:215], v246
	ds_read_b128 v[216:219], v246 offset:16
	ds_read_b128 v[220:223], v246 offset:32
	ds_read_b128 v[224:227], v246 offset:48
	ds_read_b128 v[228:231], v246 offset:64
	ds_read_b128 v[232:235], v246 offset:80
	ds_read_b128 v[236:239], v246 offset:96
	ds_read_b128 v[240:243], v246 offset:112
	s_waitcnt lgkmcnt(0)
	v_mul_f32_e32 v0, v0, v212
	v_mul_f32_e32 v1, v1, v213
	v_mul_f32_e32 v2, v2, v214
	v_mul_f32_e32 v3, v3, v215
	v_mul_f32_e32 v4, v4, v216
	v_mul_f32_e32 v5, v5, v217
	v_mul_f32_e32 v6, v6, v218
	v_mul_f32_e32 v7, v7, v219
	v_mul_f32_e32 v8, v8, v220
	v_mul_f32_e32 v9, v9, v221
	v_mul_f32_e32 v10, v10, v222
	v_mul_f32_e32 v11, v11, v223
	v_mul_f32_e32 v12, v12, v224
	v_mul_f32_e32 v13, v13, v225
	v_mul_f32_e32 v14, v14, v226
	v_mul_f32_e32 v15, v15, v227
	v_mul_f32_e32 v16, v16, v228
	v_mul_f32_e32 v17, v17, v229
	v_mul_f32_e32 v18, v18, v230
	v_mul_f32_e32 v19, v19, v231
	v_mul_f32_e32 v20, v20, v232
	v_mul_f32_e32 v21, v21, v233
	v_mul_f32_e32 v22, v22, v234
	v_mul_f32_e32 v23, v23, v235
	v_mul_f32_e32 v24, v24, v236
	v_mul_f32_e32 v25, v25, v237
	v_mul_f32_e32 v26, v26, v238
	v_mul_f32_e32 v27, v27, v239
	v_mul_f32_e32 v36, v36, v240
	v_mul_f32_e32 v28, v28, v241
	v_mul_f32_e32 v29, v29, v242
	v_mul_f32_e32 v37, v37, v243

; DI void dn_prep_item(const Params& p, int l, int item, int next_item, u32x4 (&pre)[12], unsigned char* lds, int tid) {
;     ...
;         const int chunk = (b * 8 + h) * 32 + n; unsigned char* base = p.ws + OFF_U + (size_t)chunk * PREP_CHUNK_BYTES;
;         const int f = tid >> 6, m = f >> 1, s = f & 1, r = lane & 15, g = lane >> 4, row = 16 * m + r, c0 = 32 * s + 4 * g, c1 = c0 + 16;
.LBB0_502:
	s_or_b64 exec, exec, s[6:7]
	s_setprio 0
	s_and_b32 s5, s42, 0xffffff00
	s_lshl_b32 s4, s4, 5
	s_or_b32 s4, s4, s5
	s_or_b32 s4, s4, s43
	s_ashr_i32 s5, s4, 31
	s_mul_hi_i32 s7, s4, 0xa000
	s_mul_i32 s6, s4, 0xa000
	v_mov_b64_e32 v[0:1], s[4:5]
	v_mov_b64_e32 v[58:59], s[6:7]
